# FFN-down conversion tail (live path) starts without waiting for the residual epilogue's store/atomic acknowledgements: counted wait for the trailing LDS-DMA only
# speedup vs baseline: 1.0075x; 1.0075x over previous
; __device__ __forceinline__ PItem p0_decode(const Args& a, int it) {
;     constexpr int I_IN = 16 * 96, I_OUT = 16 * 32, I_W1 = 16 * 88, I_W2 = 44 * 32, I_LAYER = I_IN + I_OUT + 2 * I_W1 + I_W2;
;     const int l = it / I_LAYER, e = l >> 1, odd = l & 1; int r = it % I_LAYER;
;     unsigned char* wl = a.ws + WS_W + (size_t)l * W_LAYER; float* cv = (float*)(a.ws + WS_CVEC) + (size_t)l * CVEC_LAYER;
;     PItem p;
;     if (r < I_IN) { const int kb = r / 96, nb = r % 96; p.W = (odd ? a.in[13] : a.in[5]) + (size_t)e * D * EIN; p.N = EIN; p.K = D; p.g = l > 0 ? a.in[21] + (size_t)(l - 1) * D : nullptr; p.be = l > 0 ? a.in[22] + (size_t)(l - 1) * D : nullptr;
;         p.WT = (bf16*)(wl + W_IN); p.drow0 = in_dst_row(32 * nb, odd); p.k0 = 64 * kb; p.n0 = 32 * nb; p.c1 = cv; p.c2 = cv + EIN; return p; } r -= I_IN;
;     if (r < I_OUT) { const int kb = r / 32, nb = r % 32; p.W = (odd ? a.in[15] : a.in[6]) + (size_t)e * D * D; p.N = D; p.K = D; p.g = nullptr; p.be = nullptr;
;         p.WT = (bf16*)(wl + W_OUT); p.drow0 = 32 * nb; p.k0 = 64 * kb; p.n0 = 32 * nb; p.c1 = nullptr; p.c2 = nullptr; return p; } r -= I_OUT;
;     if (r < 2 * I_W1) { const int second = r >= I_W1; if (second) r -= I_W1; const int kb = r / 88, nb = r % 88, n0 = 32 * nb; p.W = (second ? a.in[17] : a.in[16]) + (size_t)l * D * DFF; p.N = DFF; p.K = D;
; __global__ void __launch_bounds__(NWAVES * 64, 2) mk_fwd(Args args) {
;     ...
;                 { int Gq = F.G; asm volatile("" : "+s"(Gq)); const int nmu = g.N >> 5, mfirst = (nmu <= Gq / 2 || Gq < 256) ? (Gq - nmu > 0 ? Gq - nmu : 0) : Gq / 2; for (int mu = (int)blockIdx.x - mfirst; mu >= 0 && mu < nmu; mu += Gq - mfirst) pg8::mini_ring(F.lds + RING_OFF, g.A, g.Bt, g.K, E, mu, F.wave);
;                   if (l < 3) { if (mfirst > 0) { if ((int)blockIdx.x < mfirst) { p_convert_tail(F, args, (l + 1) * P_ILAYER, (l + 2) * P_ILAYER - ((F.G == 256) ? (l == 0 ? 768 : 1792) : 0), (int)blockIdx.x, mfirst); if (l == 0) p_state_copies_tail(F, args, (int)blockIdx.x, mfirst); } }
;                   else { p_convert_tail(F, args, (l + 1) * P_ILAYER, (l + 2) * P_ILAYER - ((F.G == 256) ? (l == 0 ? 768 : 1792) : 0), (int)blockIdx.x, F.G); if (l == 0) p_state_copies_tail(F, args, (int)blockIdx.x, F.G); } } } }
.LBB0_1546:
	s_waitcnt vmcnt(24)
	s_barrier
	v_readlane_b32 s0, v255, 62
	s_cmp_lg_u32 s0, 3
	s_mov_b64 s[10:11], -1
	v_readlane_b32 s1, v255, 63
	s_cbranch_scc0 .LBB0_1764
	s_cmp_lt_i32 s29, 33
	s_cbranch_scc0 .LBB0_1627
	v_readlane_b32 s0, v255, 62
	v_readlane_b32 s1, v255, 63
	s_mul_i32 s2, s0, 0x1880
	v_readlane_b32 s0, v255, 53
	v_readlane_b32 s1, v255, 54
	s_and_b64 s[0:1], s[0:1], exec
	s_movk_i32 s0, 0xfb00
	s_cselect_b32 s7, s0, 0xfffff500
	v_readlane_b32 s0, v252, 62
	v_readlane_b32 s1, v252, 63
	s_and_b64 s[0:1], s[0:1], exec
	s_cselect_b32 s0, s7, 0
	s_add_i32 s7, s2, s0
	v_readlane_b32 s0, v253, 60
	s_addk_i32 s7, 0x3100
	v_mbcnt_lo_u32_b32 v0, -1, 0
	v_mbcnt_hi_u32_b32 v0, -1, v0
	s_add_i32 s29, s0, s2
	v_add_u32_e32 v0, s75, v0
	s_cmp_ge_i32 s29, s7
	s_cbranch_scc1 .LBB0_1601
	s_mul_hi_i32 s0, s29, 0x5397829d
	s_lshr_b32 s1, s0, 31
	s_ashr_i32 s0, s0, 11
	s_add_i32 s26, s0, s1
	s_mul_i32 s1, s26, 0x1880
	s_ashr_i32 s30, s26, 1
	s_and_b32 s0, s26, 1
	s_sub_i32 s1, s29, s1
	s_ashr_i32 s27, s26, 31
	s_mul_i32 s10, s26, 0x1880000
	v_readlane_b32 s11, v253, 5
	s_mul_hi_i32 s2, s26, 0x1880000
	s_add_u32 s22, s11, s10
	v_readlane_b32 s10, v253, 6
	s_addc_u32 s23, s10, s2
	s_mul_i32 s10, s26, 0x11000
	v_readlane_b32 s11, v253, 7
	s_mul_hi_i32 s2, s26, 0x11000
	s_add_u32 s24, s11, s10
	v_readlane_b32 s10, v253, 8
	s_addc_u32 s25, s10, s2
	s_cmpk_gt_i32 s1, 0x5ff
	s_mov_b64 s[46:47], -1
	s_cbranch_scc0 .LBB0_1558
	s_cmpk_gt_u32 s1, 0x7ff
	s_cbranch_scc0 .LBB0_1555
	s_mov_b64 s[18:19], -1
	s_cmpk_gt_u32 s1, 0x12ff
	s_mul_hi_i32 s2, s26, 0xb00000
	s_mul_i32 s13, s26, 0xb00000
	s_cbranch_scc0 .LBB0_1553
	v_readlane_b32 s56, v253, 26
	v_readlane_b32 s57, v253, 27
	s_add_u32 s10, s56, s13
	s_addc_u32 s11, s57, s2
	s_add_u32 s14, s22, 0x1300000
	s_addc_u32 s15, s23, 0
	s_lshl_b32 s16, s1, 1
	s_lshl_b32 s12, s1, 5
	s_and_b32 s16, s16, 0x7fffffc0
	v_readlane_b32 s58, v253, 28
	v_readlane_b32 s59, v253, 29
	v_readlane_b32 s60, v253, 30
	v_readlane_b32 s61, v253, 31
	v_readlane_b32 s62, v253, 32
	v_readlane_b32 s63, v253, 33
	s_and_b32 s12, s12, 0x3e0
	s_addk_i32 s16, 0xda00
	s_mov_b64 s[18:19], 0

; #define GAS __attribute__((address_space(1)))
; #define LAS __attribute__((address_space(3)))
; #define LDS_WAIT() asm volatile("s_waitcnt lgkmcnt(0)" ::: "memory")
; __device__ __forceinline__ float bfr(float f) { return __uint_as_float(f2bf(f) << 16); }
; __device__ __forceinline__ void p0_item_load(const PItem& it, int lane, f32x4 (&v)[8]) {
; #pragma unroll
;     for (int i = 0; i < 8; ++i) v[i] = __builtin_nontemporal_load((const GAS f32x4*)(it.W + (size_t)(it.k0 + 8 * i + (lane >> 3)) * it.N + it.n0 + 4 * (lane & 7)));
; }
; __device__ __forceinline__ void p0_item_process(const PItem& it, int lane, const f32x4 (&v)[8], LAS float* scr) {
;     LAS float* gl = scr + 64 * 36 + 32; LAS float* bl = gl + 64;
;     ...
; #pragma unroll
;     for (int i = 0; i < 8; ++i) *(LAS f32x4*)(scr + SCR_ROW(8 * i + (lane >> 3)) + 4 * (lane & 7)) = v[i];
;     gl[lane] = it.g ? it.g[it.k0 + lane] : 1.f; bl[lane] = it.be ? it.be[it.k0 + lane] : 0.f;
;     LDS_WAIT(); asm volatile("" ::: "memory");
;     if (it.c1) { const int n = lane & 31, kh = lane >> 5; float s1 = 0.f, s2 = 0.f;
; #pragma unroll 8
;         for (int kk = 0; kk < 32; ++kk) { const int k = 32 * kh + kk; const float x = scr[SCR_ROW(k) + n]; s1 += bfr(gl[k] * x); s2 += bl[k] * x; }
;         s1 += __shfl_xor(s1, 32); s2 += __shfl_xor(s2, 32);
;         if (lane < 32) { atomicAdd(it.c1 + it.drow0 + n, s1); if (it.be) atomicAdd(it.c2 + it.drow0 + n, s2); } }
;     const int c = lane & 7;
;     const f32x4 g0 = *(const LAS f32x4*)(gl + 8 * c), g1 = *(const LAS f32x4*)(gl + 8 * c + 4);
; #pragma unroll
;     for (int j = 0; j < 4; ++j) { const int n = (lane >> 3) + 8 * j; const LAS float* sp = scr + SCR_ROW(8 * c) + n;
; __device__ __forceinline__ void p0_convert(const Frame& F, const Args& a, int it_lo, int it_hi, int widx, int nw, LAS float* scr) {
;     const int it0 = it_lo + widx, itend = it_hi;
;     if (it0 < itend) {
;         PItem cur = p0_decode(a, it0); f32x4 vc[8]; p0_item_load(cur, F.lane, vc);
.LBB0_1646:
	v_bfe_u32 v70, v0, 3, 3
	v_or_b32_e32 v71, 8, v70
	s_waitcnt lgkmcnt(0)
	v_add_u32_e32 v4, s16, v70
	v_ashrrev_i32_e32 v5, 31, v4
	v_add_u32_e32 v8, s16, v71
	v_and_b32_e32 v67, 63, v0
	v_mul_lo_u32 v6, s44, v5
	v_mul_lo_u32 v7, s45, v4
	v_mad_u64_u32 v[4:5], s[0:1], s44, v4, 0
	v_ashrrev_i32_e32 v9, 31, v8
	v_lshlrev_b32_e32 v3, 2, v67
	v_add3_u32 v5, v5, v6, v7
	s_ashr_i32 s35, s34, 31
	v_mul_lo_u32 v10, s44, v9
	v_mul_lo_u32 v11, s45, v8
	v_mad_u64_u32 v[8:9], s[22:23], s44, v8, 0
	v_and_b32_e32 v2, 28, v3
	v_lshl_add_u64 v[4:5], v[4:5], 2, s[10:11]
	s_lshl_b64 s[0:1], s[34:35], 2
	v_add3_u32 v9, v9, v10, v11
	v_lshl_add_u64 v[4:5], v[4:5], 0, s[0:1]
	v_lshlrev_b32_e32 v6, 2, v2
	v_mov_b32_e32 v7, v1
	v_lshl_add_u64 v[8:9], v[8:9], 2, s[10:11]
	v_or_b32_e32 v72, 16, v70
	v_lshl_add_u64 v[4:5], v[4:5], 0, v[6:7]
	v_lshl_add_u64 v[8:9], v[8:9], 0, s[0:1]
	v_lshl_add_u64 v[8:9], v[8:9], 0, v[6:7]
	global_load_dwordx4 v[58:61], v[4:5], off nt
	global_load_dwordx4 v[42:45], v[8:9], off nt
	v_add_u32_e32 v4, s16, v72
	v_ashrrev_i32_e32 v5, 31, v4
	v_or_b32_e32 v73, 24, v70
	v_mul_lo_u32 v8, s44, v5
	v_mul_lo_u32 v9, s45, v4
	v_mad_u64_u32 v[4:5], s[22:23], s44, v4, 0
	v_add3_u32 v5, v5, v8, v9
	v_add_u32_e32 v8, s16, v73
	v_ashrrev_i32_e32 v9, 31, v8
	v_mul_lo_u32 v10, s44, v9
	v_mul_lo_u32 v11, s45, v8
	v_mad_u64_u32 v[8:9], s[22:23], s44, v8, 0
	v_lshl_add_u64 v[4:5], v[4:5], 2, s[10:11]
	v_add3_u32 v9, v9, v10, v11
	v_lshl_add_u64 v[4:5], v[4:5], 0, s[0:1]
	v_lshl_add_u64 v[8:9], v[8:9], 2, s[10:11]
	v_or_b32_e32 v74, 32, v70
	v_lshl_add_u64 v[4:5], v[4:5], 0, v[6:7]
	v_lshl_add_u64 v[8:9], v[8:9], 0, s[0:1]
	v_lshl_add_u64 v[8:9], v[8:9], 0, v[6:7]
	global_load_dwordx4 v[54:57], v[4:5], off nt
	global_load_dwordx4 v[38:41], v[8:9], off nt
	v_add_u32_e32 v4, s16, v74
	v_ashrrev_i32_e32 v5, 31, v4
	v_or_b32_e32 v75, 40, v70
	v_mul_lo_u32 v8, s44, v5
	v_mul_lo_u32 v9, s45, v4
	v_mad_u64_u32 v[4:5], s[22:23], s44, v4, 0
	v_add3_u32 v5, v5, v8, v9
	v_add_u32_e32 v8, s16, v75
	v_ashrrev_i32_e32 v9, 31, v8
	v_mul_lo_u32 v10, s44, v9
	v_mul_lo_u32 v11, s45, v8
	v_mad_u64_u32 v[8:9], s[22:23], s44, v8, 0
	v_lshl_add_u64 v[4:5], v[4:5], 2, s[10:11]
	v_add3_u32 v9, v9, v10, v11
	v_lshl_add_u64 v[4:5], v[4:5], 0, s[0:1]
	v_lshl_add_u64 v[8:9], v[8:9], 2, s[10:11]
	v_or_b32_e32 v76, 48, v70
	v_lshl_add_u64 v[4:5], v[4:5], 0, v[6:7]
	v_lshl_add_u64 v[8:9], v[8:9], 0, s[0:1]
	v_lshl_add_u64 v[8:9], v[8:9], 0, v[6:7]
	global_load_dwordx4 v[50:53], v[4:5], off nt
	global_load_dwordx4 v[34:37], v[8:9], off nt
	v_add_u32_e32 v4, s16, v76
	v_ashrrev_i32_e32 v5, 31, v4
	v_or_b32_e32 v77, 56, v70
	v_mul_lo_u32 v8, s44, v5
	v_mul_lo_u32 v9, s45, v4
	v_mad_u64_u32 v[4:5], s[22:23], s44, v4, 0
	v_add3_u32 v5, v5, v8, v9
	v_add_u32_e32 v8, s16, v77
	v_ashrrev_i32_e32 v9, 31, v8
	v_mul_lo_u32 v10, s44, v9
	v_mul_lo_u32 v11, s45, v8
	v_mad_u64_u32 v[8:9], s[22:23], s44, v8, 0
	v_lshl_add_u64 v[4:5], v[4:5], 2, s[10:11]
	v_add3_u32 v9, v9, v10, v11
	v_lshl_add_u64 v[4:5], v[4:5], 0, s[0:1]
	v_lshl_add_u64 v[8:9], v[8:9], 2, s[10:11]
	v_lshl_add_u64 v[4:5], v[4:5], 0, v[6:7]
	v_lshl_add_u64 v[8:9], v[8:9], 0, s[0:1]
	v_lshl_add_u64 v[8:9], v[8:9], 0, v[6:7]
	global_load_dwordx4 v[46:49], v[4:5], off nt
	global_load_dwordx4 v[62:65], v[8:9], off nt
	v_readlane_b32 s0, v250, 6
	v_mul_u32_u24_e32 v4, 0x90, v70
	s_movk_i32 s1, 0x90
	v_add_u32_e32 v86, s0, v3
	v_lshlrev_b32_e32 v3, 3, v0
	v_add3_u32 v78, s0, v4, v6
	v_and_b32_e32 v4, 56, v3
	v_mov_b32_e32 v3, s0
	v_and_b32_e32 v66, 31, v0
	v_mad_u32_u24 v3, v4, s1, v3
	v_lshlrev_b32_e32 v5, 1, v4
	v_lshlrev_b32_e32 v6, 2, v70
	v_bfe_u32 v0, v0, 5, 1
	v_readlane_b32 s1, v254, 5
	v_add3_u32 v88, v3, v5, v6
	v_lshlrev_b32_e32 v3, 2, v66
	v_lshl_add_u32 v89, v0, 7, s1
	v_mul_u32_u24_e32 v0, 0x1240, v0
	s_lshl_b32 s41, s28, 3
	v_add_u32_e32 v79, 0x480, v78
	v_add_u32_e32 v80, 0x900, v78
	v_add_u32_e32 v81, 0xd80, v78
	v_add_u32_e32 v82, 0x1200, v78
	v_add_u32_e32 v83, 0x1680, v78
	v_add_u32_e32 v84, 0x1b00, v78
	v_add_u32_e32 v85, 0x1f80, v78
	v_cmp_gt_u32_e64 s[10:11], 32, v67
	v_lshl_add_u32 v87, v4, 2, s0
	v_add3_u32 v90, v0, v3, s0
	v_lshlrev_b32_e32 v68, 2, v2
	v_lshlrev_b32_e32 v0, 1, v4
	s_mov_b32 s2, s40
	s_mov_b64 s[24:25], s[86:87]
	s_mov_b64 s[26:27], s[84:85]
	s_mov_b64 s[22:23], s[14:15]
	s_mov_b64 s[60:61], s[20:21]
	s_mov_b64 s[30:31], s[18:19]
	s_branch .LBB0_1648
